# v50_stack
# baseline (speedup 1.0000x reference)
; #define LAS __attribute__((address_space(3)))
; DI f32x16 mfma32(bf16x8 a, bf16x8 b, f32x16 c) { return __builtin_amdgcn_mfma_f32_32x32x16_bf16(a, b, c, 0, 0, 0); }
; DI void compress_item(const Ctx& c, const Args& a, int L, int it, LAS unsigned char* lds, int wave, int lane, int tid) {
;     ...
;     for (int l = 0; l < 32; ++l) {
;         const int row = 16 * r + l, sw = (r + (l >> 4)) & 7;
; #pragma unroll
;         for (int q = 0; q < 4; ++q) {
;             const bf16x8 af = *(const bf16x8*)(Ap + 64 * l + 16 * q);
;             const bf16x8 bfr = *(const LAS bf16x8*)(lds + row * 128 + (((2 * q + h) ^ sw) << 4));
;             acc = mfma32(af, bfr, acc);
;         }
;     }
.LBB0_1134:
	v_lshl_add_u64 v[20:21], v[18:19], 0, s[14:15]
	global_load_dwordx4 v[78:81], v[20:21], off
	global_load_dwordx4 v[82:85], v[20:21], off offset:32
	global_load_dwordx4 v[86:89], v[20:21], off offset:64
	global_load_dwordx4 v[90:93], v[20:21], off offset:96
	global_load_dwordx4 v[94:97], v[20:21], off offset:128
	global_load_dwordx4 v[98:101], v[20:21], off offset:160
	global_load_dwordx4 v[102:105], v[20:21], off offset:192
	global_load_dwordx4 v[106:109], v[20:21], off offset:224
	global_load_dwordx4 v[110:113], v[20:21], off offset:256
	global_load_dwordx4 v[114:117], v[20:21], off offset:288
	global_load_dwordx4 v[118:121], v[20:21], off offset:320
	global_load_dwordx4 v[130:133], v[20:21], off offset:352
	global_load_dwordx4 v[134:137], v[20:21], off offset:384
	global_load_dwordx4 v[138:141], v[20:21], off offset:416
	global_load_dwordx4 v[142:145], v[20:21], off offset:448
	global_load_dwordx4 v[146:149], v[20:21], off offset:480
	global_load_dwordx4 v[176:179], v[20:21], off offset:512
	global_load_dwordx4 v[180:183], v[20:21], off offset:544
	global_load_dwordx4 v[184:187], v[20:21], off offset:576
	global_load_dwordx4 v[188:191], v[20:21], off offset:608
	global_load_dwordx4 v[192:195], v[20:21], off offset:640
	global_load_dwordx4 v[196:199], v[20:21], off offset:672
	global_load_dwordx4 v[200:203], v[20:21], off offset:704
	global_load_dwordx4 v[204:207], v[20:21], off offset:736
	global_load_dwordx4 v[208:211], v[20:21], off offset:768
	global_load_dwordx4 v[212:215], v[20:21], off offset:800
	global_load_dwordx4 v[216:219], v[20:21], off offset:832
	global_load_dwordx4 v[220:223], v[20:21], off offset:864
	global_load_dwordx4 v[224:227], v[20:21], off offset:896
	global_load_dwordx4 v[154:157], v[20:21], off offset:928
	global_load_dwordx4 v[158:161], v[20:21], off offset:960
	global_load_dwordx4 v[240:243], v[20:21], off offset:992
	s_lshr_b32 s13, s7, 4
	v_add_u32_e32 v37, s13, v150
	v_bitop3_b32 v26, v37, v0, 7 bitop3:0x6c
	v_lshl_add_u32 v26, v26, 4, v22
	ds_read_b128 v[38:41], v26
	v_bitop3_b32 v27, v37, v23, 7 bitop3:0x6c
	v_lshl_add_u32 v27, v27, 4, v22
	s_add_i32 s7, s7, 8
	s_add_u32 s14, s14, 0x400
	s_addc_u32 s15, s15, 0
	s_cmpk_eq_i32 s14, 0x1000
	s_waitcnt vmcnt(31) lgkmcnt(0)
	v_mfma_f32_32x32x16_bf16 v[2:17], v[78:81], v[38:41], v[2:17]
	ds_read_b128 v[38:41], v27
	s_waitcnt vmcnt(30) lgkmcnt(0)
	v_mfma_f32_32x32x16_bf16 v[2:17], v[82:85], v[38:41], v[2:17]
	v_bitop3_b32 v28, v37, v24, 7 bitop3:0x6c
	v_lshl_add_u32 v28, v28, 4, v22
	ds_read_b128 v[38:41], v28
	v_bitop3_b32 v29, v37, v25, 7 bitop3:0x6c
	v_lshl_add_u32 v29, v29, 4, v22
	v_add_u32_e32 v22, 0x400, v22
	s_waitcnt vmcnt(29) lgkmcnt(0)
	v_mfma_f32_32x32x16_bf16 v[2:17], v[86:89], v[38:41], v[2:17]
	ds_read_b128 v[38:41], v29
	s_waitcnt vmcnt(28) lgkmcnt(0)
	v_mfma_f32_32x32x16_bf16 v[2:17], v[90:93], v[38:41], v[2:17]
	ds_read_b128 v[38:41], v26 offset:128
	s_waitcnt vmcnt(27) lgkmcnt(0)
	v_mfma_f32_32x32x16_bf16 v[2:17], v[94:97], v[38:41], v[2:17]
	ds_read_b128 v[38:41], v27 offset:128
	s_waitcnt vmcnt(26) lgkmcnt(0)
	v_mfma_f32_32x32x16_bf16 v[2:17], v[98:101], v[38:41], v[2:17]
	ds_read_b128 v[38:41], v28 offset:128
	s_waitcnt vmcnt(25) lgkmcnt(0)
	v_mfma_f32_32x32x16_bf16 v[2:17], v[102:105], v[38:41], v[2:17]
	ds_read_b128 v[38:41], v29 offset:128
	s_waitcnt vmcnt(24) lgkmcnt(0)
	v_mfma_f32_32x32x16_bf16 v[2:17], v[106:109], v[38:41], v[2:17]
	ds_read_b128 v[38:41], v26 offset:256
	s_waitcnt vmcnt(23) lgkmcnt(0)
	v_mfma_f32_32x32x16_bf16 v[2:17], v[110:113], v[38:41], v[2:17]
	ds_read_b128 v[38:41], v27 offset:256
	s_waitcnt vmcnt(22) lgkmcnt(0)
	v_mfma_f32_32x32x16_bf16 v[2:17], v[114:117], v[38:41], v[2:17]
	ds_read_b128 v[38:41], v28 offset:256
	s_waitcnt vmcnt(21) lgkmcnt(0)
	v_mfma_f32_32x32x16_bf16 v[2:17], v[118:121], v[38:41], v[2:17]
	ds_read_b128 v[38:41], v29 offset:256
	s_waitcnt vmcnt(20) lgkmcnt(0)
	v_mfma_f32_32x32x16_bf16 v[2:17], v[130:133], v[38:41], v[2:17]
	ds_read_b128 v[38:41], v26 offset:384
	s_waitcnt vmcnt(19) lgkmcnt(0)
	v_mfma_f32_32x32x16_bf16 v[2:17], v[134:137], v[38:41], v[2:17]
	ds_read_b128 v[38:41], v27 offset:384
	s_waitcnt vmcnt(18) lgkmcnt(0)
	v_mfma_f32_32x32x16_bf16 v[2:17], v[138:141], v[38:41], v[2:17]
	ds_read_b128 v[38:41], v28 offset:384
	s_waitcnt vmcnt(17) lgkmcnt(0)
	v_mfma_f32_32x32x16_bf16 v[2:17], v[142:145], v[38:41], v[2:17]
	ds_read_b128 v[38:41], v29 offset:384
	s_waitcnt vmcnt(16) lgkmcnt(0)
	v_mfma_f32_32x32x16_bf16 v[2:17], v[146:149], v[38:41], v[2:17]
	ds_read_b128 v[38:41], v26 offset:512
	s_waitcnt vmcnt(15) lgkmcnt(0)
	v_mfma_f32_32x32x16_bf16 v[2:17], v[176:179], v[38:41], v[2:17]
	ds_read_b128 v[38:41], v27 offset:512
	s_waitcnt vmcnt(14) lgkmcnt(0)
	v_mfma_f32_32x32x16_bf16 v[2:17], v[180:183], v[38:41], v[2:17]
	ds_read_b128 v[38:41], v28 offset:512
	s_waitcnt vmcnt(13) lgkmcnt(0)
	v_mfma_f32_32x32x16_bf16 v[2:17], v[184:187], v[38:41], v[2:17]
	ds_read_b128 v[38:41], v29 offset:512
	s_waitcnt vmcnt(12) lgkmcnt(0)
	v_mfma_f32_32x32x16_bf16 v[2:17], v[188:191], v[38:41], v[2:17]
	ds_read_b128 v[38:41], v26 offset:640
	s_waitcnt vmcnt(11) lgkmcnt(0)
	v_mfma_f32_32x32x16_bf16 v[2:17], v[192:195], v[38:41], v[2:17]
	ds_read_b128 v[38:41], v27 offset:640
	s_waitcnt vmcnt(10) lgkmcnt(0)
	v_mfma_f32_32x32x16_bf16 v[2:17], v[196:199], v[38:41], v[2:17]
	ds_read_b128 v[38:41], v28 offset:640
	s_waitcnt vmcnt(9) lgkmcnt(0)
	v_mfma_f32_32x32x16_bf16 v[2:17], v[200:203], v[38:41], v[2:17]
	ds_read_b128 v[38:41], v29 offset:640
	s_waitcnt vmcnt(8) lgkmcnt(0)
	v_mfma_f32_32x32x16_bf16 v[2:17], v[204:207], v[38:41], v[2:17]
	ds_read_b128 v[38:41], v26 offset:768
	s_waitcnt vmcnt(7) lgkmcnt(0)
	v_mfma_f32_32x32x16_bf16 v[2:17], v[208:211], v[38:41], v[2:17]
	ds_read_b128 v[38:41], v27 offset:768
	s_waitcnt vmcnt(6) lgkmcnt(0)
	v_mfma_f32_32x32x16_bf16 v[2:17], v[212:215], v[38:41], v[2:17]
	ds_read_b128 v[38:41], v28 offset:768
	s_waitcnt vmcnt(5) lgkmcnt(0)
	v_mfma_f32_32x32x16_bf16 v[2:17], v[216:219], v[38:41], v[2:17]
	ds_read_b128 v[38:41], v29 offset:768
	s_waitcnt vmcnt(4) lgkmcnt(0)
	v_mfma_f32_32x32x16_bf16 v[2:17], v[220:223], v[38:41], v[2:17]
	ds_read_b128 v[38:41], v26 offset:896
	s_waitcnt vmcnt(3) lgkmcnt(0)
	v_mfma_f32_32x32x16_bf16 v[2:17], v[224:227], v[38:41], v[2:17]
	ds_read_b128 v[38:41], v27 offset:896
	s_waitcnt vmcnt(2) lgkmcnt(0)
	v_mfma_f32_32x32x16_bf16 v[2:17], v[154:157], v[38:41], v[2:17]
	ds_read_b128 v[38:41], v28 offset:896
	ds_read_b128 v[26:29], v29 offset:896
	s_waitcnt vmcnt(1) lgkmcnt(1)
	v_mfma_f32_32x32x16_bf16 v[2:17], v[158:161], v[38:41], v[2:17]
	s_waitcnt vmcnt(0) lgkmcnt(0)
	v_mfma_f32_32x32x16_bf16 v[2:17], v[240:243], v[26:29], v[2:17]
	s_cbranch_scc0 .LBB0_1134
; #define LAS __attribute__((address_space(3)))
; DI float ex2(float x) { return __builtin_amdgcn_exp2f(x); }
; DI f32x16 zero16() { f32x16 z; for (int i = 0; i < 16; ++i) z[i] = 0.f; return z; }
; DI void compress_item(const Ctx& c, const Args& a, int L, int it, LAS unsigned char* lds, int wave, int lane, int tid) {
;     ...
;     { const LAS float* bl = (const LAS float*)(lds + 69632) + 32 * wave + 4 * h;
; #pragma unroll
;       for (int i = 0; i < 16; ++i) acc[i] += bl[(i & 3) + 8 * (i >> 2)]; }
; #pragma unroll
;     for (int i = 0; i < 16; ++i) { const float y = acc[i]; const float u = 0.7978845608028654f * (y + 0.044715f * y * y * y); const float th = 1.f - 2.f * __builtin_amdgcn_rcpf(1.f + ex2(2.f * LOG2E * u)); acc[i] = 0.5f * y * (1.f + th); }
;     f32x16 o2[2] = {zero16(), zero16()};
;     pv_tile<64>(W2t + (size_t)r * 256 + 32 * wave + 4 * h, 256, acc, o2);
	s_and_b64 s[14:15], s[8:9], exec
	s_cselect_b32 s15, s84, s86
	s_cselect_b32 s14, s83, s85
	s_lshl_b32 s7, s12, 2
	s_add_i32 s7, s7, 0
	v_lshl_add_u32 v18, v0, 4, s7
	v_add_u32_e32 v27, 0x11000, v18
	ds_read_b128 v[18:21], v27
	ds_read_b128 v[22:25], v27 offset:32
	v_lshlrev_b32_e32 v26, 2, v0
	s_ashr_i32 s13, s12, 31
	s_movk_i32 s7, 0x4000
	s_waitcnt lgkmcnt(1)
	v_pk_add_f32 v[2:3], v[2:3], v[18:19]
	v_pk_add_f32 v[4:5], v[4:5], v[20:21]
	v_mul_f32_e32 v18, 0x3d372713, v2
	v_mul_f32_e32 v19, 0x3d372713, v3
	v_mul_f32_e32 v18, v2, v18
	v_mul_f32_e32 v19, v3, v19
	v_fma_f32 v18, v2, v18, v2
	v_fma_f32 v19, v3, v19, v3
	v_mul_f32_e32 v18, 0x3f4c422a, v18
	v_mul_f32_e32 v19, 0x3f4c422a, v19
	v_mul_f32_e32 v18, 0x4038aa3b, v18
	v_mul_f32_e32 v19, 0x4038aa3b, v19
	v_exp_f32_e32 v18, v18
	v_exp_f32_e32 v19, v19
	v_mul_f32_e32 v0, 0x3d372713, v4
	v_mul_f32_e32 v0, v4, v0
	v_mul_f32_e32 v20, 0x3d372713, v5
	v_fma_f32 v0, v4, v0, v4
	v_mul_f32_e32 v20, v5, v20
	v_add_f32_e32 v18, 1.0, v18
	v_add_f32_e32 v19, 1.0, v19
	v_mul_f32_e32 v0, 0x3f4c422a, v0
	v_fma_f32 v20, v5, v20, v5
	v_rcp_f32_e32 v18, v18
	v_rcp_f32_e32 v19, v19
	v_mul_f32_e32 v0, 0x4038aa3b, v0
	v_mul_f32_e32 v20, 0x3f4c422a, v20
	v_exp_f32_e32 v0, v0
	v_mul_f32_e32 v20, 0x4038aa3b, v20
	v_exp_f32_e32 v20, v20
	v_pk_fma_f32 v[18:19], v[18:19], 2.0, 1.0 op_sel_hi:[1,0,0] neg_lo:[1,0,0] neg_hi:[1,0,0]
	v_pk_mul_f32 v[2:3], v[2:3], 0.5 op_sel_hi:[1,0]
	v_pk_add_f32 v[18:19], v[18:19], 1.0 op_sel_hi:[1,0]
	v_add_f32_e32 v0, 1.0, v0
	v_pk_mul_f32 v[2:3], v[2:3], v[18:19]
	v_rcp_f32_e32 v18, v0
	v_add_f32_e32 v0, 1.0, v20
	s_waitcnt lgkmcnt(0)
	v_pk_add_f32 v[6:7], v[6:7], v[22:23]
	v_rcp_f32_e32 v19, v0
	v_mul_f32_e32 v0, 0x3d372713, v6
	v_mul_f32_e32 v0, v6, v0
	v_mul_f32_e32 v20, 0x3d372713, v7
	v_fma_f32 v0, v6, v0, v6
	v_mul_f32_e32 v20, v7, v20
	v_mul_f32_e32 v0, 0x3f4c422a, v0
	v_fma_f32 v20, v7, v20, v7
	v_mul_f32_e32 v0, 0x4038aa3b, v0
	v_mul_f32_e32 v20, 0x3f4c422a, v20
	v_exp_f32_e32 v0, v0
	v_mul_f32_e32 v20, 0x4038aa3b, v20
	v_exp_f32_e32 v21, v20
	v_pk_fma_f32 v[18:19], v[18:19], 2.0, 1.0 op_sel_hi:[1,0,0] neg_lo:[1,0,0] neg_hi:[1,0,0]
	v_add_f32_e32 v0, 1.0, v0
	v_rcp_f32_e32 v20, v0
	v_add_f32_e32 v0, 1.0, v21
	v_rcp_f32_e32 v21, v0
	v_pk_mul_f32 v[4:5], v[4:5], 0.5 op_sel_hi:[1,0]
	v_pk_add_f32 v[18:19], v[18:19], 1.0 op_sel_hi:[1,0]
	v_pk_mul_f32 v[6:7], v[6:7], 0.5 op_sel_hi:[1,0]
	v_pk_mul_f32 v[4:5], v[4:5], v[18:19]
	v_pk_fma_f32 v[18:19], v[20:21], 2.0, 1.0 op_sel_hi:[1,0,0] neg_lo:[1,0,0] neg_hi:[1,0,0]
	v_pk_add_f32 v[20:21], v[8:9], v[24:25]
	s_nop 0
	v_mul_f32_e32 v0, 0x3d372713, v20
	v_mul_f32_e32 v0, v20, v0
	v_mul_f32_e32 v8, 0x3d372713, v21
	v_fma_f32 v0, v20, v0, v20
	v_mul_f32_e32 v8, v21, v8
	v_mul_f32_e32 v0, 0x3f4c422a, v0
	v_fma_f32 v8, v21, v8, v21
	v_mul_f32_e32 v0, 0x4038aa3b, v0
	v_mul_f32_e32 v8, 0x3f4c422a, v8
	v_exp_f32_e32 v0, v0
	v_mul_f32_e32 v8, 0x4038aa3b, v8
	v_exp_f32_e32 v8, v8
	v_pk_mul_f32 v[28:29], v[20:21], 0.5 op_sel_hi:[1,0]
	v_add_f32_e32 v0, 1.0, v0
	v_rcp_f32_e32 v22, v0
	v_add_f32_e32 v0, 1.0, v8
	v_pk_add_f32 v[8:9], v[18:19], 1.0 op_sel_hi:[1,0]
	v_rcp_f32_e32 v23, v0
	v_pk_mul_f32 v[30:31], v[6:7], v[8:9]
	ds_read_b128 v[6:9], v27 offset:64
	v_pk_fma_f32 v[18:19], v[22:23], 2.0, 1.0 op_sel_hi:[1,0,0] neg_lo:[1,0,0] neg_hi:[1,0,0]
	s_nop 0
	v_pk_add_f32 v[32:33], v[18:19], 1.0 op_sel_hi:[1,0]
	ds_read_b128 v[18:21], v27 offset:96
	s_waitcnt lgkmcnt(1)
	v_pk_add_f32 v[6:7], v[10:11], v[6:7]
	v_ashrrev_i32_e32 v27, 31, v26
	v_mul_f32_e32 v0, 0x3d372713, v6
	v_mul_f32_e32 v0, v6, v0
	v_fma_f32 v0, v6, v0, v6
	v_mul_f32_e32 v0, 0x3f4c422a, v0
	v_mul_f32_e32 v0, 0x4038aa3b, v0
	v_exp_f32_e32 v37, v0
	v_lshlrev_b32_e32 v0, 9, v36
	v_lshl_add_u64 v[10:11], s[14:15], 0, v[0:1]
	v_lshl_add_u64 v[10:11], s[12:13], 1, v[10:11]
	v_lshl_add_u64 v[38:39], v[26:27], 1, v[10:11]
	global_load_dwordx2 v[22:23], v[38:39], off
	global_load_dwordx2 v[24:25], v[38:39], off offset:16
	v_mul_f32_e32 v0, 0x3d372713, v7
	v_mul_f32_e32 v0, v7, v0
	v_fma_f32 v0, v7, v0, v7
	v_mul_f32_e32 v0, 0x3f4c422a, v0
	v_mul_f32_e32 v0, 0x4038aa3b, v0
	v_exp_f32_e32 v0, v0
	v_pk_add_f32 v[8:9], v[12:13], v[8:9]
	v_pk_mul_f32 v[10:11], v[28:29], v[32:33]
	v_mul_f32_e32 v12, 0x3d372713, v9
	v_add_f32_e32 v0, 1.0, v0
	v_rcp_f32_e32 v33, v0
	v_mul_f32_e32 v0, 0x3d372713, v8
	v_mul_f32_e32 v0, v8, v0
	v_fma_f32 v0, v8, v0, v8
	v_mul_f32_e32 v12, v9, v12
	v_add_f32_e32 v26, 1.0, v37
	v_mul_f32_e32 v0, 0x3f4c422a, v0
	v_fma_f32 v12, v9, v12, v9
	v_rcp_f32_e32 v32, v26
	v_mul_f32_e32 v0, 0x4038aa3b, v0
	v_mul_f32_e32 v12, 0x3f4c422a, v12
	v_exp_f32_e32 v0, v0
	v_mul_f32_e32 v12, 0x4038aa3b, v12
	v_exp_f32_e32 v37, v12
	v_pk_fma_f32 v[12:13], v[32:33], 2.0, 1.0 op_sel_hi:[1,0,0] neg_lo:[1,0,0] neg_hi:[1,0,0]
	v_add_f32_e32 v0, 1.0, v0
	v_pk_mul_f32 v[6:7], v[6:7], 0.5 op_sel_hi:[1,0]
	v_pk_add_f32 v[12:13], v[12:13], 1.0 op_sel_hi:[1,0]
	v_rcp_f32_e32 v32, v0
	v_add_f32_e32 v0, 1.0, v37
	v_pk_mul_f32 v[40:41], v[6:7], v[12:13]
	s_waitcnt lgkmcnt(0)
; #define LAS __attribute__((address_space(3)))
; DI f32x16 mfma32(bf16x8 a, bf16x8 b, f32x16 c) { return __builtin_amdgcn_mfma_f32_32x32x16_bf16(a, b, c, 0, 0, 0); }
; DI float ex2(float x) { return __builtin_amdgcn_exp2f(x); }
; template <int S_> DI bf16x8 pack8(const f32x16& x) { v4u p; p.x = cvtpk(x[8 * S_], x[8 * S_ + 1]); p.y = cvtpk(x[8 * S_ + 2], x[8 * S_ + 3]); p.z = cvtpk(x[8 * S_ + 4], x[8 * S_ + 5]); p.w = cvtpk(x[8 * S_ + 6], x[8 * S_ + 7]); return __builtin_bit_cast(bf16x8, p); }
; DI f32x16 zero16() { f32x16 z; for (int i = 0; i < 16; ++i) z[i] = 0.f; return z; }
; template <int D_> DI void pv_tile(const bf16* Vp, size_t vstride, const f32x16& p, f32x16 (&o)[D_ / 32]) {
;     const bf16x8 pb0 = pack8<0>(p), pb1 = pack8<1>(p);
; #pragma unroll
;     for (int db = 0; db < D_ / 32; ++db) {
;         const bf16* vp = Vp + (size_t)db * 32 * vstride;
;         const s16x4 a0 = *(const s16x4*)(vp), a1 = *(const s16x4*)(vp + 8), b0 = *(const s16x4*)(vp + 16), b1 = *(const s16x4*)(vp + 24);
;         const bf16x8 v0 = __builtin_shufflevector(a0, a1, 0, 1, 2, 3, 4, 5, 6, 7), v1 = __builtin_shufflevector(b0, b1, 0, 1, 2, 3, 4, 5, 6, 7);
;         o[db] = mfma32(v0, pb0, o[db]); o[db] = mfma32(v1, pb1, o[db]);
;     }
; DI void compress_item(const Ctx& c, const Args& a, int L, int it, LAS unsigned char* lds, int wave, int lane, int tid) {
;     ...
;     for (int i = 0; i < 16; ++i) { const float y = acc[i]; const float u = 0.7978845608028654f * (y + 0.044715f * y * y * y); const float th = 1.f - 2.f * __builtin_amdgcn_rcpf(1.f + ex2(2.f * LOG2E * u)); acc[i] = 0.5f * y * (1.f + th); }
;     f32x16 o2[2] = {zero16(), zero16()};
;     pv_tile<64>(W2t + (size_t)r * 256 + 32 * wave + 4 * h, 256, acc, o2);
;     LAS float* red = (LAS float*)lds;
;     __syncthreads();
; #pragma unroll
;     for (int db = 0; db < 2; ++db)
; #pragma unroll
;         for (int i = 0; i < 16; ++i) red[((wave * 2 + db) * 16 + i) * 64 + lane] = o2[db][i];
;     __syncthreads();
	v_pk_add_f32 v[12:13], v[14:15], v[18:19]
	v_rcp_f32_e32 v33, v0
	v_mul_f32_e32 v0, 0x3d372713, v12
	v_mul_f32_e32 v0, v12, v0
	v_mul_f32_e32 v14, 0x3d372713, v13
	v_fma_f32 v0, v12, v0, v12
	v_mul_f32_e32 v14, v13, v14
	v_mul_f32_e32 v0, 0x3f4c422a, v0
	v_fma_f32 v14, v13, v14, v13
	v_mul_f32_e32 v0, 0x4038aa3b, v0
	v_mul_f32_e32 v14, 0x3f4c422a, v14
	v_exp_f32_e32 v0, v0
	v_mul_f32_e32 v14, 0x4038aa3b, v14
	v_exp_f32_e32 v14, v14
	v_pk_fma_f32 v[6:7], v[32:33], 2.0, 1.0 op_sel_hi:[1,0,0] neg_lo:[1,0,0] neg_hi:[1,0,0]
	v_pk_mul_f32 v[8:9], v[8:9], 0.5 op_sel_hi:[1,0]
	v_pk_add_f32 v[6:7], v[6:7], 1.0 op_sel_hi:[1,0]
	v_add_f32_e32 v0, 1.0, v0
	v_pk_mul_f32 v[32:33], v[8:9], v[6:7]
	v_rcp_f32_e32 v6, v0
	v_add_f32_e32 v0, 1.0, v14
	v_pk_add_f32 v[8:9], v[16:17], v[20:21]
	v_rcp_f32_e32 v7, v0
	v_mul_f32_e32 v0, 0x3d372713, v8
	v_mul_f32_e32 v0, v8, v0
	v_mul_f32_e32 v14, 0x3d372713, v9
	v_fma_f32 v0, v8, v0, v8
	v_mul_f32_e32 v14, v9, v14
	v_mul_f32_e32 v0, 0x3f4c422a, v0
	v_fma_f32 v14, v9, v14, v9
	v_mul_f32_e32 v0, 0x4038aa3b, v0
	v_mul_f32_e32 v14, 0x3f4c422a, v14
	v_exp_f32_e32 v0, v0
	v_mul_f32_e32 v14, 0x4038aa3b, v14
	v_exp_f32_e32 v15, v14
	v_pk_fma_f32 v[6:7], v[6:7], 2.0, 1.0 op_sel_hi:[1,0,0] neg_lo:[1,0,0] neg_hi:[1,0,0]
	v_add_f32_e32 v0, 1.0, v0
	v_rcp_f32_e32 v14, v0
	v_add_f32_e32 v0, 1.0, v15
	v_rcp_f32_e32 v15, v0
	v_pk_mul_f32 v[12:13], v[12:13], 0.5 op_sel_hi:[1,0]
	v_pk_add_f32 v[6:7], v[6:7], 1.0 op_sel_hi:[1,0]
	v_cvt_pk_bf16_f32 v20, v30, v31
	v_add_co_u32_e32 v30, vcc, s7, v38
	v_pk_mul_f32 v[42:43], v[12:13], v[6:7]
	v_pk_fma_f32 v[6:7], v[14:15], 2.0, 1.0 op_sel_hi:[1,0,0] neg_lo:[1,0,0] neg_hi:[1,0,0]
	v_cvt_pk_bf16_f32 v18, v2, v3
	v_cvt_pk_bf16_f32 v19, v4, v5
	v_cvt_pk_bf16_f32 v21, v10, v11
	v_addc_co_u32_e32 v31, vcc, 0, v39, vcc
	global_load_dwordx2 v[26:27], v[38:39], off offset:32
	global_load_dwordx2 v[28:29], v[38:39], off offset:48
	v_pk_mul_f32 v[44:45], v[8:9], 0.5 op_sel_hi:[1,0]
	v_pk_add_f32 v[46:47], v[6:7], 1.0 op_sel_hi:[1,0]
	s_waitcnt vmcnt(2)
	v_mfma_f32_32x32x16_bf16 v[2:17], v[22:25], v[18:21], 0
	global_load_dwordx2 v[22:23], v[30:31], off
	global_load_dwordx2 v[24:25], v[30:31], off offset:16
	v_mul_f32_e64 v44, v44, v46
	v_mul_f32_e64 v45, v45, v47
	v_cvt_pk_bf16_f32 v38, v40, v41
	v_cvt_pk_bf16_f32 v40, v42, v43
	v_cvt_pk_bf16_f32 v41, v44, v45
	global_load_dwordx2 v[42:43], v[30:31], off offset:32
	global_load_dwordx2 v[44:45], v[30:31], off offset:48
	v_cvt_pk_bf16_f32 v39, v32, v33
	s_lshl_b32 s7, s66, 13
	s_add_i32 s7, s7, 0
	s_waitcnt vmcnt(4)
	v_mfma_f32_32x32x16_bf16 v[2:17], v[26:29], v[38:41], v[2:17]
	v_lshl_add_u32 v0, v150, 2, s7
	s_movk_i32 s7, 0x800
	s_barrier
	v_cmp_gt_i32_e32 vcc, s7, v34
	s_waitcnt vmcnt(2)
	v_mfma_f32_32x32x16_bf16 v[18:33], v[22:25], v[18:21], 0
	s_waitcnt vmcnt(0)
	v_mfma_f32_32x32x16_bf16 v[18:33], v[42:45], v[38:41], v[18:33]
	s_nop 3
	ds_write2st64_b32 v0, v2, v3 offset1:1
	ds_write2st64_b32 v0, v4, v5 offset0:2 offset1:3
	ds_write2st64_b32 v0, v6, v7 offset0:4 offset1:5
	ds_write2st64_b32 v0, v8, v9 offset0:6 offset1:7
	ds_write2st64_b32 v0, v10, v11 offset0:8 offset1:9
	ds_write2st64_b32 v0, v12, v13 offset0:10 offset1:11
	ds_write2st64_b32 v0, v14, v15 offset0:12 offset1:13
	ds_write2st64_b32 v0, v16, v17 offset0:14 offset1:15
	ds_write2st64_b32 v0, v18, v19 offset0:16 offset1:17
	ds_write2st64_b32 v0, v20, v21 offset0:18 offset1:19
	ds_write2st64_b32 v0, v22, v23 offset0:20 offset1:21
	ds_write2st64_b32 v0, v24, v25 offset0:22 offset1:23
	ds_write2st64_b32 v0, v26, v27 offset0:24 offset1:25
	ds_write2st64_b32 v0, v28, v29 offset0:26 offset1:27
	ds_write2st64_b32 v0, v30, v31 offset0:28 offset1:29
	ds_write2st64_b32 v0, v32, v33 offset0:30 offset1:31
	v_mov_b32_e32 v6, 0
	s_waitcnt lgkmcnt(0)
	s_barrier
	s_and_saveexec_b64 s[12:13], vcc
	s_cbranch_execz .LBB0_1143
	s_ashr_i32 s7, s6, 31
	s_lshl_b64 s[14:15], s[6:7], 2
	s_lshl_b32 s16, s24, 1
	s_or_b32 s14, s14, s16
	s_lshl_b32 s16, s24, 5
	s_add_u32 s16, s16, s6
	s_addc_u32 s17, 0, s7
	s_lshl_b64 s[16:17], s[16:17], 12
	s_add_u32 s16, s67, s16
	v_lshl_or_b32 v0, s6, 5, v36
	s_movk_i32 s6, 0x3fe
	s_addc_u32 s17, s73, s17
	v_cmp_lt_i32_e64 s[6:7], s6, v0
	v_lshlrev_b32_e32 v0, 6, v36
	s_lshl_b32 s34, s66, 8
	v_and_b32_e32 v4, 3, v150
	v_and_b32_e32 v0, 0x400, v0
	s_add_i32 s34, s34, 0
	v_lshl_add_u64 v[2:3], s[40:41], 0, v[0:1]
	v_lshl_add_u32 v7, v150, 2, s34
	v_mov_b32_e32 v6, 0
	s_mov_b64 s[40:41], 0
	v_lshlrev_b32_e32 v4, 1, v4
	s_branch .LBB0_1138
